# previous best + P1 KV f32 output stores with default (write-back) policy instead of nt
# baseline (speedup 1.0000x reference)
.LBB0_243:
	s_and_b64 vcc, exec, s[10:11]
	s_cbranch_vccnz .LBB0_245
	global_store_dwordx4 v[130:131], v[122:125], off
	global_store_dwordx4 v[130:131], v[126:129], off offset:16

.LBB0_247:
	v_mov_b64_e32 v[122:123], s[24:25]
	v_mad_i64_i32 v[122:123], s[2:3], v174, s92, v[122:123]
	v_lshl_add_u64 v[122:123], s[80:81], 1, v[122:123]
	v_lshlrev_b32_e32 v142, 1, v154
	v_lshl_add_u64 v[122:123], v[122:123], 0, v[142:143]
	s_and_b64 vcc, exec, s[10:11]
	v_cvt_pk_bf16_f32 v132, v132, v133
	v_cvt_pk_bf16_f32 v133, v124, v125
	v_cvt_pk_bf16_f32 v134, v126, v127
	v_cvt_pk_bf16_f32 v135, v128, v129
	global_store_dwordx4 v[122:123], v[132:135], off sc0 sc1
	s_cbranch_vccnz .LBB0_249
	global_store_dwordx4 v[130:131], v[114:117], off offset:512
	global_store_dwordx4 v[130:131], v[118:121], off offset:528

.LBB0_255:
	s_and_b64 vcc, exec, s[10:11]
	s_cbranch_vccnz .LBB0_257
	global_store_dwordx4 v[114:115], v[106:109], off
	global_store_dwordx4 v[114:115], v[110:113], off offset:16

.LBB0_259:
	v_mov_b64_e32 v[106:107], s[24:25]
	v_mad_i64_i32 v[106:107], s[2:3], v118, s92, v[106:107]
	v_lshl_add_u64 v[106:107], s[80:81], 1, v[106:107]
	v_lshlrev_b32_e32 v142, 1, v154
	v_lshl_add_u64 v[106:107], v[106:107], 0, v[142:143]
	s_and_b64 vcc, exec, s[10:11]
	v_cvt_pk_bf16_f32 v116, v116, v117
	v_cvt_pk_bf16_f32 v117, v108, v109
	v_cvt_pk_bf16_f32 v118, v110, v111
	v_cvt_pk_bf16_f32 v119, v112, v113
	global_store_dwordx4 v[106:107], v[116:119], off sc0 sc1
	s_cbranch_vccnz .LBB0_261
	global_store_dwordx4 v[114:115], v[98:101], off offset:512
	global_store_dwordx4 v[114:115], v[102:105], off offset:528

.LBB0_267:
	s_and_b64 vcc, exec, s[10:11]
	s_cbranch_vccnz .LBB0_269
	global_store_dwordx4 v[98:99], v[90:93], off
	global_store_dwordx4 v[98:99], v[94:97], off offset:16

.LBB0_271:
	v_mov_b64_e32 v[90:91], s[24:25]
	v_mad_i64_i32 v[90:91], s[2:3], v102, s92, v[90:91]
	v_lshl_add_u64 v[90:91], s[80:81], 1, v[90:91]
	v_lshlrev_b32_e32 v142, 1, v154
	v_lshl_add_u64 v[90:91], v[90:91], 0, v[142:143]
	s_and_b64 vcc, exec, s[10:11]
	v_cvt_pk_bf16_f32 v100, v100, v101
	v_cvt_pk_bf16_f32 v101, v92, v93
	v_cvt_pk_bf16_f32 v102, v94, v95
	v_cvt_pk_bf16_f32 v103, v96, v97
	global_store_dwordx4 v[90:91], v[100:103], off sc0 sc1
	s_cbranch_vccnz .LBB0_273
	global_store_dwordx4 v[98:99], v[82:85], off offset:512
	global_store_dwordx4 v[98:99], v[86:89], off offset:528

.LBB0_279:
	s_and_b64 vcc, exec, s[10:11]
	s_cbranch_vccnz .LBB0_281
	global_store_dwordx4 v[82:83], v[74:77], off
	global_store_dwordx4 v[82:83], v[78:81], off offset:16

.LBB0_283:
	v_mov_b64_e32 v[74:75], s[24:25]
	v_mad_i64_i32 v[74:75], s[2:3], v86, s92, v[74:75]
	v_lshl_add_u64 v[74:75], s[80:81], 1, v[74:75]
	v_lshlrev_b32_e32 v142, 1, v154
	v_lshl_add_u64 v[74:75], v[74:75], 0, v[142:143]
	s_and_b64 vcc, exec, s[10:11]
	v_cvt_pk_bf16_f32 v84, v84, v85
	v_cvt_pk_bf16_f32 v85, v76, v77
	v_cvt_pk_bf16_f32 v86, v78, v79
	v_cvt_pk_bf16_f32 v87, v80, v81
	global_store_dwordx4 v[74:75], v[84:87], off sc0 sc1
	s_cbranch_vccnz .LBB0_285
	global_store_dwordx4 v[82:83], v[66:69], off offset:512
	global_store_dwordx4 v[82:83], v[70:73], off offset:528

.LBB0_291:
	s_and_b64 vcc, exec, s[10:11]
	s_cbranch_vccnz .LBB0_293
	global_store_dwordx4 v[50:51], v[42:45], off
	global_store_dwordx4 v[50:51], v[46:49], off offset:16

.LBB0_295:
	v_mov_b64_e32 v[42:43], s[24:25]
	v_mad_i64_i32 v[42:43], s[2:3], v54, s92, v[42:43]
	v_lshl_add_u64 v[42:43], s[80:81], 1, v[42:43]
	v_lshlrev_b32_e32 v142, 1, v154
	v_lshl_add_u64 v[42:43], v[42:43], 0, v[142:143]
	s_and_b64 vcc, exec, s[10:11]
	v_cvt_pk_bf16_f32 v52, v52, v53
	v_cvt_pk_bf16_f32 v53, v44, v45
	v_cvt_pk_bf16_f32 v54, v46, v47
	v_cvt_pk_bf16_f32 v55, v48, v49
	global_store_dwordx4 v[42:43], v[52:55], off sc0 sc1
	s_cbranch_vccnz .LBB0_297
	global_store_dwordx4 v[50:51], v[34:37], off offset:512
	global_store_dwordx4 v[50:51], v[38:41], off offset:528

.LBB0_304:
	s_and_b64 vcc, exec, s[10:11]
	s_cbranch_vccnz .LBB0_306
	global_store_dwordx4 v[66:67], v[58:61], off
	global_store_dwordx4 v[66:67], v[62:65], off offset:16

.LBB0_308:
	v_mov_b64_e32 v[58:59], s[24:25]
	v_mad_i64_i32 v[58:59], s[2:3], v70, s92, v[58:59]
	v_lshl_add_u64 v[58:59], s[80:81], 1, v[58:59]
	v_lshlrev_b32_e32 v142, 1, v154
	v_lshl_add_u64 v[58:59], v[58:59], 0, v[142:143]
	s_and_b64 vcc, exec, s[10:11]
	v_cvt_pk_bf16_f32 v68, v68, v69
	v_cvt_pk_bf16_f32 v69, v60, v61
	v_cvt_pk_bf16_f32 v70, v62, v63
	v_cvt_pk_bf16_f32 v71, v64, v65
	global_store_dwordx4 v[58:59], v[68:71], off sc0 sc1
	s_cbranch_vccnz .LBB0_310
	global_store_dwordx4 v[66:67], v[50:53], off offset:512
	global_store_dwordx4 v[66:67], v[54:57], off offset:528

.LBB0_316:
	s_and_b64 vcc, exec, s[10:11]
	s_cbranch_vccnz .LBB0_318
	global_store_dwordx4 v[34:35], v[26:29], off
	global_store_dwordx4 v[34:35], v[30:33], off offset:16

.LBB0_320:
	v_mov_b64_e32 v[26:27], s[24:25]
	v_mad_i64_i32 v[26:27], s[2:3], v38, s92, v[26:27]
	v_lshl_add_u64 v[26:27], s[80:81], 1, v[26:27]
	v_lshlrev_b32_e32 v142, 1, v154
	v_lshl_add_u64 v[26:27], v[26:27], 0, v[142:143]
	s_and_b64 vcc, exec, s[10:11]
	v_cvt_pk_bf16_f32 v36, v36, v37
	v_cvt_pk_bf16_f32 v37, v28, v29
	v_cvt_pk_bf16_f32 v38, v30, v31
	v_cvt_pk_bf16_f32 v39, v32, v33
	global_store_dwordx4 v[26:27], v[36:39], off sc0 sc1
	s_cbranch_vccnz .LBB0_322
	global_store_dwordx4 v[34:35], v[18:21], off offset:512
	global_store_dwordx4 v[34:35], v[22:25], off offset:528

.LBB0_327:
	s_and_b64 vcc, exec, s[10:11]
	s_cbranch_vccnz .LBB0_329
	global_store_dwordx4 v[18:19], v[10:13], off
	global_store_dwordx4 v[18:19], v[14:17], off offset:16

.LBB0_331:
	v_mov_b64_e32 v[10:11], s[24:25]
	v_mad_i64_i32 v[10:11], s[2:3], v22, s92, v[10:11]
	v_lshl_add_u64 v[10:11], s[80:81], 1, v[10:11]
	v_lshlrev_b32_e32 v142, 1, v154
	v_lshl_add_u64 v[10:11], v[10:11], 0, v[142:143]
	s_and_b64 vcc, exec, s[10:11]
	v_cvt_pk_bf16_f32 v20, v20, v21
	v_cvt_pk_bf16_f32 v21, v12, v13
	v_cvt_pk_bf16_f32 v22, v14, v15
	v_cvt_pk_bf16_f32 v23, v16, v17
	global_store_dwordx4 v[10:11], v[20:23], off sc0 sc1
	s_cbranch_vccnz .LBB0_333
	global_store_dwordx4 v[18:19], v[2:5], off offset:512
	global_store_dwordx4 v[18:19], v[6:9], off offset:528
